# p3a: record-store acks no longer waited inside the kk loop (per-wave-class vmcnt), next-unit rows loaded straight into their staging registers without a drain
# baseline (speedup 1.0000x reference)
.LBB0_497:
	s_andn2_saveexec_b64 s[0:1], s[0:1]
	v_lshl_add_u32 v2, s5, 9, v3
	s_or_b64 exec, exec, s[0:1]
	v_ashrrev_i32_e32 v3, 31, v2
	v_lshl_add_u64 v[20:21], v[2:3], 2, s[56:57]
	s_mov_b32 s1, 0x8000
	v_add_co_u32_e32 v10, vcc, s1, v20
	s_mov_b32 s1, 0x10000
	s_nop 0
	v_addc_co_u32_e32 v11, vcc, 0, v21, vcc
	v_add_co_u32_e32 v66, vcc, s1, v20
	s_ashr_i32 s85, s4, 3
	s_nop 0
	v_addc_co_u32_e32 v67, vcc, 0, v21, vcc
	s_mov_b32 s1, 0x18000
	s_bfe_u32 s7, s4, 0x10002
	s_lshl_b32 s0, s85, 6
	s_lshl_b32 s84, s5, 2
	v_add_co_u32_e32 v68, vcc, s1, v20
	v_readlane_b32 s1, v249, 56
	v_writelane_b32 v248, s5, 20
	s_or_b32 s73, s84, 1
	s_add_i32 s5, s1, s0
	s_lshl_b32 s1, s7, 12
	s_add_i32 s8, s8, 1
	s_cmp_lt_i32 s8, s10
	s_cselect_b64 s[86:87], -1, 0
	s_add_i32 s4, s4, s81
	s_lshl_b32 s2, s4, 2
	s_and_b32 s2, s2, 12
	s_lshl_b32 s3, s2, 8
	v_writelane_b32 v248, s8, 21
	s_addk_i32 s3, 0xf00
	v_writelane_b32 v248, s3, 22
	s_lshl_b32 s2, s2, 7
	v_writelane_b32 v248, s2, 23
	s_addk_i32 s2, 0x780
	v_writelane_b32 v248, s2, 24
	s_and_b32 s2, s4, 0x1ffffff8
	v_readlane_b32 s3, v249, 49
	s_add_i32 s2, s2, s3
	s_lshl_b32 s6, s2, 3
	s_lshl_b32 s2, s4, 10
	s_and_b32 s4, s2, 0x1000
	s_ashr_i32 s2, s0, 31
	s_add_u32 s88, s1, s0
	s_addc_u32 s89, 0, s2
	s_ashr_i32 s2, s85, 31
	s_lshl_b32 s72, s7, 5
	v_writelane_b32 v248, s2, 25
	s_lshl_b32 s2, s7, 10
	s_cmp_gt_i32 s5, -1
	v_writelane_b32 v248, s7, 26
	s_cselect_b64 s[90:91], -1, 0
	s_add_i32 s7, s5, s1
	s_cmp_gt_i32 s5, -2
	v_writelane_b32 v248, s2, 27
	s_mul_i32 s92, s7, 0xa600
	s_cselect_b64 s[94:95], -1, 0
	s_add_i32 s2, s7, 1
	s_mul_hi_u32 s3, s2, 0xa600
	s_add_i32 s2, s92, 0xa600
	v_writelane_b32 v248, s2, 28
	s_mul_hi_u32 s93, s7, 0xa600
	v_addc_co_u32_e32 v69, vcc, 0, v21, vcc
	v_writelane_b32 v248, s3, 29
	s_or_b32 s2, s7, 2
	s_mul_hi_u32 s35, s2, 0xa600
	s_mul_i32 s34, s2, 0xa600
	v_readlane_b32 s2, v249, 55
	s_add_i32 s0, s0, s2
	s_cmp_gt_i32 s0, -1
	s_cselect_b64 s[24:25], -1, 0
	s_add_i32 s0, s0, s1
	s_cmp_gt_i32 s5, -5
	s_mul_hi_u32 s69, s0, 0xa600
	s_mul_i32 s68, s0, 0xa600
	s_cselect_b64 s[38:39], -1, 0
	s_add_i32 s0, s7, 4
	s_mul_hi_u32 s1, s0, 0xa600
	s_add_i32 s0, s92, 0x29800
	v_writelane_b32 v248, s0, 30
	s_cmp_gt_i32 s5, -6
	s_cselect_b64 s[26:27], -1, 0
	v_writelane_b32 v248, s1, 31
	s_add_i32 s0, s7, 5
	s_add_i32 s78, s92, 0x33e00
	s_cmp_gt_i32 s5, -7
	s_mul_hi_u32 s79, s0, 0xa600
	s_cselect_b64 s[2:3], -1, 0
	s_add_i32 s0, s7, 6
	s_add_i32 s76, s92, 0x3e400
	s_cmp_gt_i32 s5, -8
	s_mul_hi_u32 s77, s0, 0xa600
	s_cselect_b64 s[30:31], -1, 0
	s_add_i32 s0, s7, 7
	s_mul_hi_u32 s1, s0, 0xa600
	s_add_i32 s0, s92, 0x48a00
	s_cmp_gt_i32 s5, -9
	s_cselect_b64 s[36:37], -1, 0
	s_add_i32 s8, s7, 8
	s_add_i32 s44, s92, 0x53000
	s_cmp_gt_i32 s5, -10
	s_mul_hi_u32 s45, s8, 0xa600
	s_cselect_b64 s[50:51], -1, 0
	s_add_i32 s8, s7, 9
	s_add_i32 s74, s92, 0x5d600
	s_cmp_gt_i32 s5, -11
	s_cselect_b64 s[22:23], -1, 0
	s_add_i32 s7, s7, 10
	s_add_i32 s66, s92, 0x67c00
	s_cmp_gt_i32 s6, 2
	s_mul_hi_u32 s75, s8, 0xa600
	s_cselect_b64 s[8:9], -1, 0
	s_add_i32 s4, s6, s4
	v_writelane_b32 v248, s8, 32
	s_add_i32 s5, s4, -3
	s_mul_i32 s80, s4, 0xa600
	v_writelane_b32 v248, s9, 33
	s_mul_hi_u32 s9, s5, 0xa600
	s_add_i32 s8, s80, 0xfffe0e00
	v_writelane_b32 v248, s8, 34
	s_cmp_gt_i32 s6, 1
	s_mul_hi_u32 s67, s7, 0xa600
	v_writelane_b32 v248, s9, 35
	s_cselect_b64 s[8:9], -1, 0
	v_writelane_b32 v248, s8, 36
	s_add_i32 s5, s4, -2
	s_mul_hi_u32 s81, s4, 0xa600
	v_writelane_b32 v248, s9, 37
	s_mul_hi_u32 s9, s5, 0xa600
	s_add_i32 s8, s80, 0xfffeb400
	v_writelane_b32 v248, s8, 38
	s_cmp_gt_i32 s6, 0
	global_load_dwordx4 v[2:5], v[20:21], off offset:16
	global_load_dwordx4 v[6:9], v[20:21], off
	v_writelane_b32 v248, s9, 39
	s_cselect_b64 s[8:9], -1, 0
	v_writelane_b32 v248, s8, 40
	s_add_i32 s5, s4, -1
	s_waitcnt vmcnt(4)
	v_mov_b64_e32 v[116:117], v[24:25]
	v_writelane_b32 v248, s9, 41
	s_add_i32 s8, s80, 0xffff5a00
	s_mul_hi_u32 s9, s5, 0xa600
	s_cmp_gt_i32 s6, -1
	v_writelane_b32 v248, s8, 42
	s_cselect_b64 s[82:83], -1, 0
	s_or_b32 s5, s4, 1
	v_writelane_b32 v248, s9, 43
	s_mul_hi_u32 s7, s5, 0xa600
	s_mul_i32 s6, s5, 0xa600
	v_writelane_b32 v248, s6, 44
	s_or_b32 s5, s4, 2
	s_waitcnt vmcnt(3)
	v_mov_b64_e32 v[120:121], v[28:29]
	v_writelane_b32 v248, s7, 45
	s_mul_hi_u32 s7, s5, 0xa600
	s_mul_i32 s6, s5, 0xa600
	v_writelane_b32 v248, s6, 46
	s_or_b32 s5, s4, 3
	s_waitcnt vmcnt(2)
	v_mov_b64_e32 v[124:125], v[32:33]
	v_writelane_b32 v248, s7, 47
	s_mul_hi_u32 s7, s5, 0xa600
	s_mul_i32 s6, s5, 0xa600
	v_writelane_b32 v248, s6, 48
	s_or_b32 s5, s4, 4
	v_mov_b64_e32 v[128:129], v[36:37]
	v_writelane_b32 v248, s7, 49
	s_mul_hi_u32 s7, s5, 0xa600
	s_mul_i32 s6, s5, 0xa600
	v_writelane_b32 v248, s6, 50
	s_or_b32 s5, s4, 5
	v_mov_b64_e32 v[132:133], v[40:41]
	v_writelane_b32 v248, s7, 51
	s_mul_hi_u32 s7, s5, 0xa600
	s_mul_i32 s6, s5, 0xa600
	v_writelane_b32 v248, s6, 52
	s_or_b32 s5, s4, 6
	s_or_b32 s4, s4, 7
	v_writelane_b32 v248, s7, 53
	s_mul_hi_u32 s7, s5, 0xa600
	s_mul_i32 s6, s5, 0xa600
	v_writelane_b32 v248, s6, 54
	s_mul_hi_u32 s5, s4, 0xa600
	s_mul_i32 s4, s4, 0xa600
	v_writelane_b32 v248, s7, 55
	v_writelane_b32 v248, s4, 56
	v_mov_b64_e32 v[136:137], v[44:45]
	v_mov_b64_e32 v[140:141], v[48:49]
	v_writelane_b32 v248, s5, 57
	s_mov_b64 s[4:5], 0x8000
	v_lshl_add_u64 v[14:15], v[20:21], 0, s[4:5]
	s_mov_b64 s[4:5], 0x10000
	v_lshl_add_u64 v[70:71], v[20:21], 0, s[4:5]
	s_mov_b64 s[4:5], 0x18000
	global_load_dwordx4 v[10:13], v[10:11], off
	s_nop 0
	global_load_dwordx4 v[14:17], v[14:15], off offset:16
	s_nop 0
	global_load_dwordx4 v[98:101], v[66:67], off
	global_load_dwordx4 v[102:105], v[70:71], off offset:16
	v_lshl_add_u64 v[20:21], v[20:21], 0, s[4:5]
	global_load_dwordx4 v[106:109], v[68:69], off
	global_load_dwordx4 v[110:113], v[20:21], off offset:16
	v_mov_b64_e32 v[144:145], v[52:53]
	v_mov_b64_e32 v[148:149], v[56:57]
	v_mov_b64_e32 v[152:153], v[60:61]
	v_mov_b64_e32 v[156:157], v[64:65]
	v_mov_b64_e32 v[114:115], v[22:23]
	v_mov_b64_e32 v[118:119], v[26:27]
	v_mov_b64_e32 v[122:123], v[30:31]
	v_mov_b64_e32 v[126:127], v[34:35]
	v_mov_b64_e32 v[130:131], v[38:39]
	v_mov_b64_e32 v[134:135], v[42:43]
	v_mov_b64_e32 v[138:139], v[46:47]
	v_mov_b64_e32 v[142:143], v[50:51]
	v_mov_b64_e32 v[146:147], v[54:55]
	v_mov_b64_e32 v[150:151], v[58:59]
	v_mov_b64_e32 v[154:155], v[62:63]
	s_mov_b32 s64, 0
	s_waitcnt vmcnt(0)
.LBB0_500:
	v_lshlrev_b32_e32 v20, 16, v114
	v_and_b32_e32 v21, 0xffff0000, v114
	v_lshlrev_b32_e32 v34, 16, v118
	v_and_b32_e32 v35, 0xffff0000, v118
	v_pk_fma_f32 v[20:21], v[6:7], v[20:21], 0 op_sel_hi:[1,1,0]
	v_lshlrev_b32_e32 v42, 16, v122
	v_and_b32_e32 v43, 0xffff0000, v122
	v_pk_fma_f32 v[20:21], v[10:11], v[34:35], v[20:21]
	v_lshlrev_b32_e32 v50, 16, v126
	v_and_b32_e32 v51, 0xffff0000, v126
	v_pk_fma_f32 v[20:21], v[98:99], v[42:43], v[20:21]
	v_lshlrev_b32_e32 v32, 16, v119
	v_pk_fma_f32 v[20:21], v[106:107], v[50:51], v[20:21]
	v_and_b32_e32 v33, 0xffff0000, v119
	v_mul_f32_e32 v22, 0xbfb8aa3b, v20
	v_mul_f32_e32 v23, 0xbfb8aa3b, v21
	v_exp_f32_e32 v22, v22
	v_exp_f32_e32 v23, v23
	v_lshlrev_b32_e32 v40, 16, v123
	v_and_b32_e32 v41, 0xffff0000, v123
	v_add_f32_e32 v22, 1.0, v22
	v_add_f32_e32 v23, 1.0, v23
	v_rcp_f32_e32 v22, v22
	v_rcp_f32_e32 v23, v23
	v_lshlrev_b32_e32 v46, 16, v127
	v_and_b32_e32 v47, 0xffff0000, v127
	v_lshlrev_b32_e32 v52, 16, v116
	v_pk_mul_f32 v[20:21], v[20:21], v[22:23]
	v_lshlrev_b32_e32 v22, 16, v115
	v_and_b32_e32 v23, 0xffff0000, v115
	v_pk_fma_f32 v[22:23], v[8:9], v[22:23], 0 op_sel_hi:[1,1,0]
	v_and_b32_e32 v53, 0xffff0000, v116
	v_pk_fma_f32 v[22:23], v[12:13], v[32:33], v[22:23]
	v_lshlrev_b32_e32 v30, 16, v120
	v_pk_fma_f32 v[22:23], v[100:101], v[40:41], v[22:23]
	v_and_b32_e32 v31, 0xffff0000, v120
	v_pk_fma_f32 v[22:23], v[108:109], v[46:47], v[22:23]
	v_pk_fma_f32 v[52:53], v[2:3], v[52:53], 0 op_sel_hi:[1,1,0]
	v_mul_f32_e32 v24, 0xbfb8aa3b, v22
	v_exp_f32_e32 v26, v24
	v_mul_f32_e32 v24, 0xbfb8aa3b, v23
	v_exp_f32_e32 v27, v24
	v_lshlrev_b32_e32 v38, 16, v124
	v_and_b32_e32 v39, 0xffff0000, v124
	v_pk_fma_f32 v[52:53], v[14:15], v[30:31], v[52:53]
	v_lshlrev_b32_e32 v48, 16, v128
	v_and_b32_e32 v49, 0xffff0000, v128
	v_pk_fma_f32 v[52:53], v[102:103], v[38:39], v[52:53]
	v_add_f32_e32 v26, 1.0, v26
	s_and_b64 s[100:101], s[96:97], exec
	s_cbranch_scc0 .Lp3a_s2h_skip
	s_or_b32 s98, s64, s84
	s_lshl_b32 s98, s98, 1
	v_readlane_b32 s99, v249, 49
	v_readlane_b32 s100, v249, 47
	v_readlane_b32 s101, v249, 48
	v_mov_b32_e32 v244, v1
	v_mov_b32_e32 v245, 0
	s_or_b32 s98, s98, s99
	s_lshl_b32 s98, s98, 2
	v_lshl_add_u64 v[244:245], s[88:89], 0, v[244:245]
	s_add_u32 s100, s100, s98
	s_addc_u32 s101, s101, 0
	v_lshlrev_b64 v[244:245], 8, v[244:245]
	s_nop 1
	v_lshl_add_u64 v[244:245], s[100:101], 0, v[244:245]
	s_add_u32 s100, s60, s98
	s_addc_u32 s101, s61, 0
	global_load_dword v240, v[244:245], off
	global_load_dword v241, v[244:245], off offset:128
	global_load_dword v242, v18, s[100:101]
	s_add_u32 s100, s58, s98
	s_addc_u32 s101, s59, 0
	global_load_dword v243, v18, s[100:101]

.LBB0_565:
	s_or_b64 exec, exec, s[8:9]
	v_readlane_b32 s8, v248, 32
	v_readlane_b32 s9, v248, 33
	s_andn2_b64 vcc, exec, s[8:9]
	v_readlane_b32 s8, v249, 43
	v_ashrrev_i32_e32 v21, 31, v20
	v_readlane_b32 s9, v249, 44
	s_nop 0
	v_lshl_add_u64 v[226:227], v[20:21], 1, s[8:9]
	s_cbranch_vccnz .LBB0_588
	v_readlane_b32 s8, v248, 34
	v_readlane_b32 s9, v248, 35
	s_nop 1
	v_lshl_add_u64 v[20:21], v[226:227], 0, s[8:9]
	global_load_dwordx4 v[22:25], v[20:21], off
	s_branch .LBB0_589

.LBB0_587:
	s_andn2_b64 vcc, exec, s[96:97]
	s_or_b32 s42, s64, s84
	s_cbranch_vccz .LBB0_612
	s_branch .LBB0_615
.LBB0_588:
	v_mov_b32_e32 v20, v18
	v_mov_b32_e32 v21, v18
	v_mov_b32_e32 v19, v18
	v_mov_b64_e32 v[24:25], v[20:21]
	v_mov_b64_e32 v[22:23], v[18:19]
.LBB0_589:
	v_readlane_b32 s8, v248, 36
	v_readlane_b32 s9, v248, 37
	s_andn2_b64 vcc, exec, s[8:9]
	s_cbranch_vccnz .LBB0_591
	v_readlane_b32 s8, v248, 38
	v_readlane_b32 s9, v248, 39
	s_nop 1
	v_lshl_add_u64 v[20:21], v[226:227], 0, s[8:9]
	global_load_dwordx4 v[26:29], v[20:21], off
	s_branch .LBB0_592

.LBB0_592:
	v_readlane_b32 s8, v248, 40
	v_readlane_b32 s9, v248, 41
	s_andn2_b64 vcc, exec, s[8:9]
	s_cbranch_vccnz .LBB0_602
	v_readlane_b32 s8, v248, 42
	v_readlane_b32 s9, v248, 43
	s_nop 1
	v_lshl_add_u64 v[20:21], v[226:227], 0, s[8:9]
	global_load_dwordx4 v[30:33], v[20:21], off
	v_cndmask_b32_e64 v19, 0, 1, s[82:83]
	v_cmp_ne_u32_e64 s[8:9], 1, v19
	s_andn2_b64 vcc, exec, s[82:83]
	s_cbranch_vccnz .LBB0_603
.LBB0_594:
	v_lshl_add_u64 v[20:21], v[226:227], 0, s[80:81]
	global_load_dwordx4 v[34:37], v[20:21], off
	s_and_b64 vcc, exec, s[8:9]
	s_cbranch_vccnz .LBB0_604
.LBB0_595:
	v_readlane_b32 s10, v248, 44
	v_readlane_b32 s11, v248, 45
	s_nop 1
	v_lshl_add_u64 v[20:21], v[226:227], 0, s[10:11]
	global_load_dwordx4 v[38:41], v[20:21], off
	s_and_b64 vcc, exec, s[8:9]
	s_cbranch_vccnz .LBB0_605
.LBB0_596:
	v_readlane_b32 s10, v248, 46
	v_readlane_b32 s11, v248, 47
	s_nop 1
	v_lshl_add_u64 v[20:21], v[226:227], 0, s[10:11]
	global_load_dwordx4 v[42:45], v[20:21], off
	s_and_b64 vcc, exec, s[8:9]
	s_cbranch_vccnz .LBB0_606
.LBB0_597:
	v_readlane_b32 s10, v248, 48
	v_readlane_b32 s11, v248, 49
	s_nop 1
	v_lshl_add_u64 v[20:21], v[226:227], 0, s[10:11]
	global_load_dwordx4 v[46:49], v[20:21], off
	s_and_b64 vcc, exec, s[8:9]
	s_cbranch_vccnz .LBB0_607
.LBB0_598:
	v_readlane_b32 s10, v248, 50
	v_readlane_b32 s11, v248, 51
	s_nop 1
	v_lshl_add_u64 v[20:21], v[226:227], 0, s[10:11]
	global_load_dwordx4 v[50:53], v[20:21], off
	s_and_b64 vcc, exec, s[8:9]
	s_cbranch_vccnz .LBB0_608
.LBB0_599:
	v_readlane_b32 s10, v248, 52
	v_readlane_b32 s11, v248, 53
	s_nop 1
	v_lshl_add_u64 v[20:21], v[226:227], 0, s[10:11]
	global_load_dwordx4 v[54:57], v[20:21], off
	s_and_b64 vcc, exec, s[8:9]
	s_cbranch_vccnz .LBB0_609
.LBB0_600:
	v_readlane_b32 s10, v248, 54
	v_readlane_b32 s11, v248, 55
	s_nop 1
	v_lshl_add_u64 v[20:21], v[226:227], 0, s[10:11]
	global_load_dwordx4 v[58:61], v[20:21], off
	s_and_b64 vcc, exec, s[8:9]
	s_cbranch_vccnz .LBB0_610
.LBB0_601:
	v_readlane_b32 s8, v248, 56
	v_readlane_b32 s9, v248, 57
	s_nop 1
	v_lshl_add_u64 v[20:21], v[226:227], 0, s[8:9]
	global_load_dwordx4 v[62:65], v[20:21], off
	s_branch .LBB0_611
.LBB0_602:
	v_mov_b32_e32 v20, v18
	v_mov_b32_e32 v21, v18
	v_mov_b32_e32 v19, v18
	v_mov_b64_e32 v[32:33], v[20:21]
	v_mov_b64_e32 v[30:31], v[18:19]
	v_cndmask_b32_e64 v19, 0, 1, s[82:83]
	v_cmp_ne_u32_e64 s[8:9], 1, v19
	s_andn2_b64 vcc, exec, s[82:83]
	s_cbranch_vccz .LBB0_594
.LBB0_603:
	v_mov_b32_e32 v20, v18
	v_mov_b32_e32 v21, v18
	v_mov_b32_e32 v19, v18
	v_mov_b64_e32 v[36:37], v[20:21]
	v_mov_b64_e32 v[34:35], v[18:19]
	s_and_b64 vcc, exec, s[8:9]
	s_cbranch_vccz .LBB0_595
.LBB0_604:
	v_mov_b32_e32 v20, v18
	v_mov_b32_e32 v21, v18
	v_mov_b32_e32 v19, v18
	v_mov_b64_e32 v[40:41], v[20:21]
	v_mov_b64_e32 v[38:39], v[18:19]
	s_and_b64 vcc, exec, s[8:9]
	s_cbranch_vccz .LBB0_596
.LBB0_605:
	v_mov_b32_e32 v20, v18
	v_mov_b32_e32 v21, v18
	v_mov_b32_e32 v19, v18
	v_mov_b64_e32 v[44:45], v[20:21]
	v_mov_b64_e32 v[42:43], v[18:19]
	s_and_b64 vcc, exec, s[8:9]
	s_cbranch_vccz .LBB0_597
.LBB0_606:
	v_mov_b32_e32 v20, v18
	v_mov_b32_e32 v21, v18
	v_mov_b32_e32 v19, v18
	v_mov_b64_e32 v[48:49], v[20:21]
	v_mov_b64_e32 v[46:47], v[18:19]
	s_and_b64 vcc, exec, s[8:9]
	s_cbranch_vccz .LBB0_598
.LBB0_607:
	v_mov_b32_e32 v20, v18
	v_mov_b32_e32 v21, v18
	v_mov_b32_e32 v19, v18
	v_mov_b64_e32 v[52:53], v[20:21]
	v_mov_b64_e32 v[50:51], v[18:19]
	s_and_b64 vcc, exec, s[8:9]
	s_cbranch_vccz .LBB0_599
.LBB0_608:
	v_mov_b32_e32 v20, v18
	v_mov_b32_e32 v21, v18
	v_mov_b32_e32 v19, v18
	v_mov_b64_e32 v[56:57], v[20:21]
	v_mov_b64_e32 v[54:55], v[18:19]
	s_and_b64 vcc, exec, s[8:9]
	s_cbranch_vccz .LBB0_600
.LBB0_609:
	v_mov_b32_e32 v20, v18
	v_mov_b32_e32 v21, v18
	v_mov_b32_e32 v19, v18
	v_mov_b64_e32 v[60:61], v[20:21]
	v_mov_b64_e32 v[58:59], v[18:19]
	s_and_b64 vcc, exec, s[8:9]
	s_cbranch_vccz .LBB0_601

.LBB0_611:
	v_mov_b64_e32 v[72:73], v[8:9]
	v_mov_b64_e32 v[68:69], v[4:5]
	v_mov_b64_e32 v[76:77], v[12:13]
	v_mov_b64_e32 v[80:81], v[16:17]
	v_mov_b64_e32 v[82:83], v[98:99]
	v_mov_b64_e32 v[86:87], v[102:103]
	v_mov_b64_e32 v[90:91], v[106:107]
	v_mov_b64_e32 v[94:95], v[110:111]
	v_mov_b64_e32 v[70:71], v[6:7]
	v_mov_b64_e32 v[66:67], v[2:3]
	v_mov_b64_e32 v[74:75], v[10:11]
	v_mov_b64_e32 v[78:79], v[14:15]
	v_mov_b64_e32 v[84:85], v[100:101]
	v_mov_b64_e32 v[88:89], v[104:105]
	v_mov_b64_e32 v[92:93], v[108:109]
	v_mov_b64_e32 v[96:97], v[112:113]
	s_andn2_b64 vcc, exec, s[96:97]
	s_or_b32 s42, s64, s84
	s_cbranch_vccnz .LBB0_615

.LBB0_651:
	s_add_i32 s64, s64, 1
	s_cmp_eq_u32 s64, 4
	s_waitcnt lgkmcnt(0)
	s_barrier
	s_cbranch_scc1 .LBB0_653
	v_readlane_b32 s98, v249, 49
	s_nop 0
	s_and_b32 s99, s98, 3
	s_cmp_eq_u32 s99, 3
	s_cbranch_scc1 .Lp3a_bw_copy
	s_cmp_gt_u32 s98, 3
	s_cbranch_scc1 .Lp3a_bw_qk
	s_cmp_gt_u32 s98, 1
	s_cbranch_scc1 .Lp3a_bw_all
	s_waitcnt vmcnt(2)
	s_branch .Lp3a_bw_done
.Lp3a_bw_all:
	s_waitcnt vmcnt(0)
	s_branch .Lp3a_bw_done
.Lp3a_bw_qk:
	s_waitcnt vmcnt(4)
	s_branch .Lp3a_bw_done
.Lp3a_bw_copy:
	s_waitcnt vmcnt(32)
.Lp3a_bw_done:
	v_mov_b64_e32 v[6:7], v[70:71]
	v_mov_b64_e32 v[2:3], v[66:67]
	v_mov_b64_e32 v[10:11], v[74:75]
	v_mov_b64_e32 v[14:15], v[78:79]
	v_mov_b64_e32 v[100:101], v[84:85]
	v_mov_b64_e32 v[104:105], v[88:89]
	v_mov_b64_e32 v[108:109], v[92:93]
	v_mov_b64_e32 v[112:113], v[96:97]
	v_mov_b64_e32 v[116:117], v[24:25]
	v_mov_b64_e32 v[120:121], v[28:29]
	v_mov_b64_e32 v[124:125], v[32:33]
	v_mov_b64_e32 v[128:129], v[36:37]
	v_mov_b64_e32 v[132:133], v[40:41]
	v_mov_b64_e32 v[136:137], v[44:45]
	v_mov_b64_e32 v[140:141], v[48:49]
	v_mov_b64_e32 v[144:145], v[52:53]
	v_mov_b64_e32 v[148:149], v[56:57]
	v_mov_b64_e32 v[152:153], v[60:61]
	v_mov_b64_e32 v[156:157], v[64:65]
	v_mov_b64_e32 v[8:9], v[72:73]
	v_mov_b64_e32 v[4:5], v[68:69]
	v_mov_b64_e32 v[12:13], v[76:77]
	v_mov_b64_e32 v[16:17], v[80:81]
	v_mov_b64_e32 v[98:99], v[82:83]
	v_mov_b64_e32 v[102:103], v[86:87]
	v_mov_b64_e32 v[106:107], v[90:91]
	v_mov_b64_e32 v[110:111], v[94:95]
	v_mov_b64_e32 v[114:115], v[22:23]
	v_mov_b64_e32 v[118:119], v[26:27]
	v_mov_b64_e32 v[122:123], v[30:31]
	v_mov_b64_e32 v[126:127], v[34:35]
	v_mov_b64_e32 v[130:131], v[38:39]
	v_mov_b64_e32 v[134:135], v[42:43]
	v_mov_b64_e32 v[138:139], v[46:47]
	v_mov_b64_e32 v[142:143], v[50:51]
	v_mov_b64_e32 v[146:147], v[54:55]
	v_mov_b64_e32 v[150:151], v[58:59]
	v_mov_b64_e32 v[154:155], v[62:63]
	s_branch .LBB0_500
